# scan step loop rewritten: 4-way DPP row_ror operand sharing (LDS reads/step 20->5 b128), plain v_fmac instead of pk, double-buffered LDS prefetch
# speedup vs baseline: 1.0065x; 1.0065x over previous
; __device__ __forceinline__ float red4(float x) { x += dppf(x, 0); x += dppf(x, 1); return x; }
; __device__ __forceinline__ void scan_phase(const Params& p, int j, unsigned char* smem) {
;     ...
;             __syncthreads();
; #pragma unroll 2
;             for (int t = 0; t < 16; ++t) {
;                 const float* op = OPS + t * 320 + kq * 16;
;                 f32x4 A4[4], B4[4], W4[4], K4[4], R4[4];
; #pragma unroll
;                 for (int i = 0; i < 4; ++i) A4[i] = *(const f32x4*)(op + i * 4);
; #pragma unroll
;                 for (int i = 0; i < 4; ++i) { W4[i] = *(const f32x4*)(op + 128 + i * 4); B4[i] = *(const f32x4*)(op + 64 + i * 4); K4[i] = *(const f32x4*)(op + 192 + i * 4); }
; #pragma unroll
;                 for (int i = 0; i < 4; ++i) R4[i] = *(const f32x4*)(op + 256 + i * 4);
;                 const float vv = VB[t * 64 + vrow];
;                 f32x2 s0 = {0.f, 0.f}, s1 = {0.f, 0.f};
; #pragma unroll
;                 for (int i = 0; i < 4; ++i) { s0 += S[2 * i] * (f32x2){A4[i][0], A4[i][1]}; s1 += S[2 * i + 1] * (f32x2){A4[i][2], A4[i][3]}; }
;                 const float sa = red4((s0[0] + s0[1]) + (s1[0] + s1[1]));
;                 const f32x2 sa2 = {sa, sa}, vv2 = {vv, vv};
; #pragma unroll
;                 for (int i = 0; i < 4; ++i) {
;                     S[2 * i] = S[2 * i] * (f32x2){W4[i][0], W4[i][1]} + sa2 * (f32x2){B4[i][0], B4[i][1]} + vv2 * (f32x2){K4[i][0], K4[i][1]};
;                     S[2 * i + 1] = S[2 * i + 1] * (f32x2){W4[i][2], W4[i][3]} + sa2 * (f32x2){B4[i][2], B4[i][3]} + vv2 * (f32x2){K4[i][2], K4[i][3]};
;                 }
;                 f32x2 y0 = {0.f, 0.f}, y1 = {0.f, 0.f};
; #pragma unroll
;                 for (int i = 0; i < 4; ++i) { y0 += S[2 * i] * (f32x2){R4[i][0], R4[i][1]}; y1 += S[2 * i + 1] * (f32x2){R4[i][2], R4[i][3]}; }
;                 const float y = red4((y0[0] + y0[1]) + (y1[0] + y1[1]));
;                 if (kq == 0) YB[t * 64 + vrow] = y;
;             }
.LBB0_509:
	v_lshlrev_b32_e32 v66, 2, v226
	v_and_b32_e32 v66, 48, v66
	v_add3_u32 v64, v23, v59, v66
	v_lshl_add_u32 v65, s10, 2, v62
	s_movk_i32 s7, 0xf000
	s_waitcnt lgkmcnt(0)
	s_barrier
	v_add_u32_e32 v66, s7, v65
	ds_read_b128 v[68:71], v64
	ds_read_b128 v[72:75], v64 offset:256
	ds_read_b128 v[76:79], v64 offset:512
	ds_read_b128 v[80:83], v64 offset:768
	ds_read_b128 v[84:87], v64 offset:1024
	ds_read_b32 v88, v66 offset:24576
	ds_read_b128 v[92:95], v64 offset:1280
	ds_read_b128 v[96:99], v64 offset:1536
	ds_read_b128 v[100:103], v64 offset:1792
	ds_read_b128 v[104:107], v64 offset:2048
	ds_read_b128 v[108:111], v64 offset:2304
	ds_read_b32 v112, v66 offset:24832
	ds_read_b32 v122, v66 offset:24576
	s_branch .LBB0_511
.LBB0_510:
	s_addk_i32 s7, 0x200
	s_cmp_eq_u32 s7, 0
	v_add_u32_e32 v64, 0xa00, v64
	s_cbranch_scc1 .LBB0_504
.LBB0_511:
	v_add_u32_e32 v66, s7, v65
	s_waitcnt lgkmcnt(7)
	v_mul_f32_e32 v113, v68, v38
	v_mul_f32_e32 v114, v69, v39
	v_mul_f32_e32 v115, v70, v40
	v_mul_f32_e32 v116, v71, v41
	v_fmac_f32_dpp v113, v68, v42 row_ror:4 row_mask:0xf bank_mask:0xf
	v_fmac_f32_dpp v114, v69, v43 row_ror:4 row_mask:0xf bank_mask:0xf
	v_fmac_f32_dpp v115, v70, v44 row_ror:4 row_mask:0xf bank_mask:0xf
	v_fmac_f32_dpp v116, v71, v45 row_ror:4 row_mask:0xf bank_mask:0xf
	v_fmac_f32_dpp v113, v68, v46 row_ror:8 row_mask:0xf bank_mask:0xf
	v_fmac_f32_dpp v114, v69, v47 row_ror:8 row_mask:0xf bank_mask:0xf
	v_fmac_f32_dpp v115, v70, v48 row_ror:8 row_mask:0xf bank_mask:0xf
	v_fmac_f32_dpp v116, v71, v49 row_ror:8 row_mask:0xf bank_mask:0xf
	v_fmac_f32_dpp v113, v68, v50 row_ror:12 row_mask:0xf bank_mask:0xf
	v_fmac_f32_dpp v114, v69, v51 row_ror:12 row_mask:0xf bank_mask:0xf
	v_fmac_f32_dpp v115, v70, v52 row_ror:12 row_mask:0xf bank_mask:0xf
	v_fmac_f32_dpp v116, v71, v53 row_ror:12 row_mask:0xf bank_mask:0xf
	v_add_f32_e32 v113, v113, v114
	v_add_f32_e32 v115, v115, v116
	v_add_f32_e32 v113, v113, v115
	v_mul_f32_e32 v38, v76, v38
	v_mul_f32_e32 v39, v77, v39
	v_add_f32_dpp v114, v113, v113 quad_perm:[1,0,3,2] row_mask:0xf bank_mask:0xf bound_ctrl:1
	v_mul_f32_e32 v40, v78, v40
	v_mul_f32_e32 v41, v79, v41
	v_add_f32_dpp v117, v114, v114 quad_perm:[2,3,0,1] row_mask:0xf bank_mask:0xf bound_ctrl:1
	v_mul_f32_dpp v42, v76, v42 row_ror:4 row_mask:0xf bank_mask:0xf
	v_mul_f32_dpp v43, v77, v43 row_ror:4 row_mask:0xf bank_mask:0xf
	v_mul_f32_dpp v44, v78, v44 row_ror:4 row_mask:0xf bank_mask:0xf
	v_mul_f32_dpp v45, v79, v45 row_ror:4 row_mask:0xf bank_mask:0xf
	v_mul_f32_dpp v46, v76, v46 row_ror:8 row_mask:0xf bank_mask:0xf
	v_mul_f32_dpp v47, v77, v47 row_ror:8 row_mask:0xf bank_mask:0xf
	v_mul_f32_dpp v48, v78, v48 row_ror:8 row_mask:0xf bank_mask:0xf
	v_mul_f32_dpp v49, v79, v49 row_ror:8 row_mask:0xf bank_mask:0xf
	v_mul_f32_dpp v50, v76, v50 row_ror:12 row_mask:0xf bank_mask:0xf
	v_mul_f32_dpp v51, v77, v51 row_ror:12 row_mask:0xf bank_mask:0xf
	v_mul_f32_dpp v52, v78, v52 row_ror:12 row_mask:0xf bank_mask:0xf
	v_mul_f32_dpp v53, v79, v53 row_ror:12 row_mask:0xf bank_mask:0xf
	v_fmac_f32_e32 v38, v72, v117
	v_fmac_f32_e32 v39, v73, v117
	v_fmac_f32_e32 v40, v74, v117
	v_fmac_f32_e32 v41, v75, v117
	v_fmac_f32_dpp v42, v72, v117 row_ror:4 row_mask:0xf bank_mask:0xf
	v_fmac_f32_dpp v43, v73, v117 row_ror:4 row_mask:0xf bank_mask:0xf
	v_fmac_f32_dpp v44, v74, v117 row_ror:4 row_mask:0xf bank_mask:0xf
	v_fmac_f32_dpp v45, v75, v117 row_ror:4 row_mask:0xf bank_mask:0xf
	v_fmac_f32_dpp v46, v72, v117 row_ror:8 row_mask:0xf bank_mask:0xf
	v_fmac_f32_dpp v47, v73, v117 row_ror:8 row_mask:0xf bank_mask:0xf
	v_fmac_f32_dpp v48, v74, v117 row_ror:8 row_mask:0xf bank_mask:0xf
	v_fmac_f32_dpp v49, v75, v117 row_ror:8 row_mask:0xf bank_mask:0xf
	v_fmac_f32_dpp v50, v72, v117 row_ror:12 row_mask:0xf bank_mask:0xf
	v_fmac_f32_dpp v51, v73, v117 row_ror:12 row_mask:0xf bank_mask:0xf
	v_fmac_f32_dpp v52, v74, v117 row_ror:12 row_mask:0xf bank_mask:0xf
	v_fmac_f32_dpp v53, v75, v117 row_ror:12 row_mask:0xf bank_mask:0xf
	v_fmac_f32_e32 v38, v80, v88
	v_fmac_f32_e32 v39, v81, v88
	v_fmac_f32_e32 v40, v82, v88
	v_fmac_f32_e32 v41, v83, v88
	v_fmac_f32_dpp v42, v80, v88 row_ror:4 row_mask:0xf bank_mask:0xf
	v_fmac_f32_dpp v43, v81, v88 row_ror:4 row_mask:0xf bank_mask:0xf
	v_fmac_f32_dpp v44, v82, v88 row_ror:4 row_mask:0xf bank_mask:0xf
	v_fmac_f32_dpp v45, v83, v88 row_ror:4 row_mask:0xf bank_mask:0xf
	v_fmac_f32_dpp v46, v80, v88 row_ror:8 row_mask:0xf bank_mask:0xf
	v_fmac_f32_dpp v47, v81, v88 row_ror:8 row_mask:0xf bank_mask:0xf
	v_fmac_f32_dpp v48, v82, v88 row_ror:8 row_mask:0xf bank_mask:0xf
	v_fmac_f32_dpp v49, v83, v88 row_ror:8 row_mask:0xf bank_mask:0xf
	v_fmac_f32_dpp v50, v80, v88 row_ror:12 row_mask:0xf bank_mask:0xf
	v_fmac_f32_dpp v51, v81, v88 row_ror:12 row_mask:0xf bank_mask:0xf
	v_fmac_f32_dpp v52, v82, v88 row_ror:12 row_mask:0xf bank_mask:0xf
	v_fmac_f32_dpp v53, v83, v88 row_ror:12 row_mask:0xf bank_mask:0xf
	v_mul_f32_e32 v118, v84, v38
	v_mul_f32_e32 v119, v85, v39
	v_mul_f32_e32 v120, v86, v40
	v_mul_f32_e32 v121, v87, v41
	v_fmac_f32_dpp v118, v84, v42 row_ror:4 row_mask:0xf bank_mask:0xf
	v_fmac_f32_dpp v119, v85, v43 row_ror:4 row_mask:0xf bank_mask:0xf
	v_fmac_f32_dpp v120, v86, v44 row_ror:4 row_mask:0xf bank_mask:0xf
	v_fmac_f32_dpp v121, v87, v45 row_ror:4 row_mask:0xf bank_mask:0xf
	v_fmac_f32_dpp v118, v84, v46 row_ror:8 row_mask:0xf bank_mask:0xf
	v_fmac_f32_dpp v119, v85, v47 row_ror:8 row_mask:0xf bank_mask:0xf
	v_fmac_f32_dpp v120, v86, v48 row_ror:8 row_mask:0xf bank_mask:0xf
	v_fmac_f32_dpp v121, v87, v49 row_ror:8 row_mask:0xf bank_mask:0xf
	v_fmac_f32_dpp v118, v84, v50 row_ror:12 row_mask:0xf bank_mask:0xf
	v_fmac_f32_dpp v119, v85, v51 row_ror:12 row_mask:0xf bank_mask:0xf
	v_fmac_f32_dpp v120, v86, v52 row_ror:12 row_mask:0xf bank_mask:0xf
	v_fmac_f32_dpp v121, v87, v53 row_ror:12 row_mask:0xf bank_mask:0xf
	v_add_f32_e32 v118, v118, v119
	v_add_f32_e32 v120, v120, v121
	v_add_f32_e32 v118, v118, v120
	ds_read_b128 v[68:71], v64 offset:2560
	ds_read_b128 v[72:75], v64 offset:2816
	ds_read_b128 v[76:79], v64 offset:3072
	v_add_f32_dpp v119, v118, v118 quad_perm:[1,0,3,2] row_mask:0xf bank_mask:0xf bound_ctrl:1
	ds_read_b128 v[80:83], v64 offset:3328
	ds_read_b128 v[84:87], v64 offset:3584
	ds_read_b32 v88, v66 offset:25088
	v_add_f32_dpp v120, v119, v119 quad_perm:[2,3,0,1] row_mask:0xf bank_mask:0xf bound_ctrl:1
	s_and_saveexec_b64 s[2:3], s[4:5]
	ds_write_b32 v66, v120 offset:32768
	s_or_b64 exec, exec, s[2:3]
	s_waitcnt lgkmcnt(7)
; __device__ __forceinline__ float red4(float x) { x += dppf(x, 0); x += dppf(x, 1); return x; }
; __device__ __forceinline__ void scan_phase(const Params& p, int j, unsigned char* smem) {
;     ...
;             for (int t = 0; t < 16; ++t) {
;                 const float* op = OPS + t * 320 + kq * 16;
;                 f32x4 A4[4], B4[4], W4[4], K4[4], R4[4];
; #pragma unroll
;                 for (int i = 0; i < 4; ++i) A4[i] = *(const f32x4*)(op + i * 4);
; #pragma unroll
;                 for (int i = 0; i < 4; ++i) { W4[i] = *(const f32x4*)(op + 128 + i * 4); B4[i] = *(const f32x4*)(op + 64 + i * 4); K4[i] = *(const f32x4*)(op + 192 + i * 4); }
; #pragma unroll
;                 for (int i = 0; i < 4; ++i) R4[i] = *(const f32x4*)(op + 256 + i * 4);
;                 const float vv = VB[t * 64 + vrow];
;                 f32x2 s0 = {0.f, 0.f}, s1 = {0.f, 0.f};
; #pragma unroll
;                 for (int i = 0; i < 4; ++i) { s0 += S[2 * i] * (f32x2){A4[i][0], A4[i][1]}; s1 += S[2 * i + 1] * (f32x2){A4[i][2], A4[i][3]}; }
;                 const float sa = red4((s0[0] + s0[1]) + (s1[0] + s1[1]));
;                 const f32x2 sa2 = {sa, sa}, vv2 = {vv, vv};
; #pragma unroll
;                 for (int i = 0; i < 4; ++i) {
;                     S[2 * i] = S[2 * i] * (f32x2){W4[i][0], W4[i][1]} + sa2 * (f32x2){B4[i][0], B4[i][1]} + vv2 * (f32x2){K4[i][0], K4[i][1]};
;                     S[2 * i + 1] = S[2 * i + 1] * (f32x2){W4[i][2], W4[i][3]} + sa2 * (f32x2){B4[i][2], B4[i][3]} + vv2 * (f32x2){K4[i][2], K4[i][3]};
;                 }
;                 f32x2 y0 = {0.f, 0.f}, y1 = {0.f, 0.f};
; #pragma unroll
;                 for (int i = 0; i < 4; ++i) { y0 += S[2 * i] * (f32x2){R4[i][0], R4[i][1]}; y1 += S[2 * i + 1] * (f32x2){R4[i][2], R4[i][3]}; }
;                 const float y = red4((y0[0] + y0[1]) + (y1[0] + y1[1]));
;                 if (kq == 0) YB[t * 64 + vrow] = y;
;             }
	v_mul_f32_e32 v113, v92, v38
	v_mul_f32_e32 v114, v93, v39
	v_mul_f32_e32 v115, v94, v40
	v_mul_f32_e32 v116, v95, v41
	v_fmac_f32_dpp v113, v92, v42 row_ror:4 row_mask:0xf bank_mask:0xf
	v_fmac_f32_dpp v114, v93, v43 row_ror:4 row_mask:0xf bank_mask:0xf
	v_fmac_f32_dpp v115, v94, v44 row_ror:4 row_mask:0xf bank_mask:0xf
	v_fmac_f32_dpp v116, v95, v45 row_ror:4 row_mask:0xf bank_mask:0xf
	v_fmac_f32_dpp v113, v92, v46 row_ror:8 row_mask:0xf bank_mask:0xf
	v_fmac_f32_dpp v114, v93, v47 row_ror:8 row_mask:0xf bank_mask:0xf
	v_fmac_f32_dpp v115, v94, v48 row_ror:8 row_mask:0xf bank_mask:0xf
	v_fmac_f32_dpp v116, v95, v49 row_ror:8 row_mask:0xf bank_mask:0xf
	v_fmac_f32_dpp v113, v92, v50 row_ror:12 row_mask:0xf bank_mask:0xf
	v_fmac_f32_dpp v114, v93, v51 row_ror:12 row_mask:0xf bank_mask:0xf
	v_fmac_f32_dpp v115, v94, v52 row_ror:12 row_mask:0xf bank_mask:0xf
	v_fmac_f32_dpp v116, v95, v53 row_ror:12 row_mask:0xf bank_mask:0xf
	v_add_f32_e32 v113, v113, v114
	v_add_f32_e32 v115, v115, v116
	v_add_f32_e32 v113, v113, v115
	v_mul_f32_e32 v38, v100, v38
	v_mul_f32_e32 v39, v101, v39
	v_add_f32_dpp v114, v113, v113 quad_perm:[1,0,3,2] row_mask:0xf bank_mask:0xf bound_ctrl:1
	v_mul_f32_e32 v40, v102, v40
	v_mul_f32_e32 v41, v103, v41
	v_add_f32_dpp v117, v114, v114 quad_perm:[2,3,0,1] row_mask:0xf bank_mask:0xf bound_ctrl:1
	v_mul_f32_dpp v42, v100, v42 row_ror:4 row_mask:0xf bank_mask:0xf
	v_mul_f32_dpp v43, v101, v43 row_ror:4 row_mask:0xf bank_mask:0xf
	v_mul_f32_dpp v44, v102, v44 row_ror:4 row_mask:0xf bank_mask:0xf
	v_mul_f32_dpp v45, v103, v45 row_ror:4 row_mask:0xf bank_mask:0xf
	v_mul_f32_dpp v46, v100, v46 row_ror:8 row_mask:0xf bank_mask:0xf
	v_mul_f32_dpp v47, v101, v47 row_ror:8 row_mask:0xf bank_mask:0xf
	v_mul_f32_dpp v48, v102, v48 row_ror:8 row_mask:0xf bank_mask:0xf
	v_mul_f32_dpp v49, v103, v49 row_ror:8 row_mask:0xf bank_mask:0xf
	v_mul_f32_dpp v50, v100, v50 row_ror:12 row_mask:0xf bank_mask:0xf
	v_mul_f32_dpp v51, v101, v51 row_ror:12 row_mask:0xf bank_mask:0xf
	v_mul_f32_dpp v52, v102, v52 row_ror:12 row_mask:0xf bank_mask:0xf
	v_mul_f32_dpp v53, v103, v53 row_ror:12 row_mask:0xf bank_mask:0xf
	v_fmac_f32_e32 v38, v96, v117
	v_fmac_f32_e32 v39, v97, v117
	v_fmac_f32_e32 v40, v98, v117
	v_fmac_f32_e32 v41, v99, v117
	v_fmac_f32_dpp v42, v96, v117 row_ror:4 row_mask:0xf bank_mask:0xf
	v_fmac_f32_dpp v43, v97, v117 row_ror:4 row_mask:0xf bank_mask:0xf
	v_fmac_f32_dpp v44, v98, v117 row_ror:4 row_mask:0xf bank_mask:0xf
	v_fmac_f32_dpp v45, v99, v117 row_ror:4 row_mask:0xf bank_mask:0xf
	v_fmac_f32_dpp v46, v96, v117 row_ror:8 row_mask:0xf bank_mask:0xf
	v_fmac_f32_dpp v47, v97, v117 row_ror:8 row_mask:0xf bank_mask:0xf
	v_fmac_f32_dpp v48, v98, v117 row_ror:8 row_mask:0xf bank_mask:0xf
	v_fmac_f32_dpp v49, v99, v117 row_ror:8 row_mask:0xf bank_mask:0xf
	v_fmac_f32_dpp v50, v96, v117 row_ror:12 row_mask:0xf bank_mask:0xf
	v_fmac_f32_dpp v51, v97, v117 row_ror:12 row_mask:0xf bank_mask:0xf
	v_fmac_f32_dpp v52, v98, v117 row_ror:12 row_mask:0xf bank_mask:0xf
	v_fmac_f32_dpp v53, v99, v117 row_ror:12 row_mask:0xf bank_mask:0xf
	v_fmac_f32_e32 v38, v104, v112
	v_fmac_f32_e32 v39, v105, v112
	v_fmac_f32_e32 v40, v106, v112
	v_fmac_f32_e32 v41, v107, v112
	v_fmac_f32_dpp v42, v104, v112 row_ror:4 row_mask:0xf bank_mask:0xf
	v_fmac_f32_dpp v43, v105, v112 row_ror:4 row_mask:0xf bank_mask:0xf
	v_fmac_f32_dpp v44, v106, v112 row_ror:4 row_mask:0xf bank_mask:0xf
	v_fmac_f32_dpp v45, v107, v112 row_ror:4 row_mask:0xf bank_mask:0xf
	v_fmac_f32_dpp v46, v104, v112 row_ror:8 row_mask:0xf bank_mask:0xf
	v_fmac_f32_dpp v47, v105, v112 row_ror:8 row_mask:0xf bank_mask:0xf
	v_fmac_f32_dpp v48, v106, v112 row_ror:8 row_mask:0xf bank_mask:0xf
	v_fmac_f32_dpp v49, v107, v112 row_ror:8 row_mask:0xf bank_mask:0xf
	v_fmac_f32_dpp v50, v104, v112 row_ror:12 row_mask:0xf bank_mask:0xf
	v_fmac_f32_dpp v51, v105, v112 row_ror:12 row_mask:0xf bank_mask:0xf
	v_fmac_f32_dpp v52, v106, v112 row_ror:12 row_mask:0xf bank_mask:0xf
	v_fmac_f32_dpp v53, v107, v112 row_ror:12 row_mask:0xf bank_mask:0xf
	v_mul_f32_e32 v118, v108, v38
	v_mul_f32_e32 v119, v109, v39
	v_mul_f32_e32 v120, v110, v40
	v_mul_f32_e32 v121, v111, v41
	v_fmac_f32_dpp v118, v108, v42 row_ror:4 row_mask:0xf bank_mask:0xf
	v_fmac_f32_dpp v119, v109, v43 row_ror:4 row_mask:0xf bank_mask:0xf
	v_fmac_f32_dpp v120, v110, v44 row_ror:4 row_mask:0xf bank_mask:0xf
	v_fmac_f32_dpp v121, v111, v45 row_ror:4 row_mask:0xf bank_mask:0xf
	v_fmac_f32_dpp v118, v108, v46 row_ror:8 row_mask:0xf bank_mask:0xf
	v_fmac_f32_dpp v119, v109, v47 row_ror:8 row_mask:0xf bank_mask:0xf
	v_fmac_f32_dpp v120, v110, v48 row_ror:8 row_mask:0xf bank_mask:0xf
	v_fmac_f32_dpp v121, v111, v49 row_ror:8 row_mask:0xf bank_mask:0xf
	v_fmac_f32_dpp v118, v108, v50 row_ror:12 row_mask:0xf bank_mask:0xf
	v_fmac_f32_dpp v119, v109, v51 row_ror:12 row_mask:0xf bank_mask:0xf
	v_fmac_f32_dpp v120, v110, v52 row_ror:12 row_mask:0xf bank_mask:0xf
	v_fmac_f32_dpp v121, v111, v53 row_ror:12 row_mask:0xf bank_mask:0xf
	v_add_f32_e32 v118, v118, v119
	v_add_f32_e32 v120, v120, v121
	v_add_f32_e32 v118, v118, v120
	ds_read_b128 v[92:95], v64 offset:3840
	ds_read_b128 v[96:99], v64 offset:4096
	ds_read_b128 v[100:103], v64 offset:4352
	v_add_f32_dpp v119, v118, v118 quad_perm:[1,0,3,2] row_mask:0xf bank_mask:0xf bound_ctrl:1
	ds_read_b128 v[104:107], v64 offset:4608
	ds_read_b128 v[108:111], v64 offset:4864
	ds_read_b32 v112, v66 offset:25344
	v_add_f32_dpp v120, v119, v119 quad_perm:[2,3,0,1] row_mask:0xf bank_mask:0xf bound_ctrl:1
	s_and_saveexec_b64 s[2:3], s[4:5]
	ds_write_b32 v66, v120 offset:33024
	s_or_b64 exec, exec, s[2:3]
	s_branch .LBB0_510
